# meta-token row GEMMs: 32 operand loads in flight with counted waits instead of 16 serialized load-wait-MFMA steps (both instances)
# speedup vs baseline: 1.0138x; 1.0028x over previous
; DI size_t zrowU(int row0, int NT) { return ((size_t)((row0 >> 8) * NT) << 16) + (size_t)((((row0 >> 7) & 1) << 15) | (((row0 >> 5) & 1) << 14) | (((row0 >> 6) & 1) << 11)); }
; DI unsigned zlaneRC(int r5, int col) { return (unsigned)(((col >> 8) << 16) | ((r5 >> 4) << 13) | (((col >> 7) & 1) << 12) | (((col >> 5) & 3) << 9) | (((col >> 3) & 3) << 7) | ((r5 & 15) << 3) | (col & 7)); }
; template <bool TILED_IN>
; DI void meta_gemm(const bf16_t* am, int lda, const bf16_t* Wt, int N, bf16_t* zo, int ldzo, int nt, LAS unsigned char* lds, int bid, int G, int wave, int lane) {
;     ...
;     for (int t0 = 2 * (G - 1 - bid); t0 < ntasks; t0 += 2 * G) {
;         const int task = t0 + (wave >> 2), n0 = task * 16;
;         const bf16_t* ap = Wt + (size_t)(n0 + r) * D + 8 * q + 512 * kq;
;         const bf16_t* bp = TILED_IN ? am + zrowU(SEQ, nt) + zlaneRC(r, 512 * kq + 8 * q) : am + (size_t)r * lda + 8 * q + 512 * kq;
;         f32x4 acc = {0.f, 0.f, 0.f, 0.f};
;         if (task < ntasks) {
; #pragma unroll
;             for (int k = 0; k < 16; ++k) { const bf16x8 a = *(const bf16x8*)(ap + 32 * k);
;                 const bf16x8 b = *(const bf16x8*)(bp + (TILED_IN ? (((k >> 3) << 16) | (((k >> 2) & 1) << 12) | ((k & 3) << 9)) : 32 * k));
;                 acc = __builtin_amdgcn_mfma_f32_16x16x32_bf16(a, b, acc, 0, 0, 0); }
;         }
.LBB0_70:
	s_add_i32 s8, s26, s24
	s_cmp_ge_i32 s8, s25
	s_cselect_b64 s[8:9], -1, 0
	v_mov_b32_e32 v2, 0
	s_and_b64 vcc, exec, s[8:9]
	v_mov_b32_e32 v3, 0
	v_mov_b32_e32 v4, 0
	v_mov_b32_e32 v5, 0
	s_cbranch_vccnz .LBB0_72
	v_ashrrev_i32_e32 v11, 31, v10
	v_lshlrev_b64 v[2:3], 12, v[10:11]
	v_lshl_add_u64 v[26:27], v[6:7], 0, v[2:3]
	global_load_dwordx4 v[28:31], v[26:27], off
	global_load_dwordx4 v[92:95], v[8:9], off
	global_load_dwordx4 v[32:35], v[26:27], off offset:64
	global_load_dwordx4 v[96:99], v[8:9], off offset:64
	global_load_dwordx4 v[36:39], v[26:27], off offset:128
	global_load_dwordx4 v[100:103], v[8:9], off offset:128
	global_load_dwordx4 v[40:43], v[26:27], off offset:192
	global_load_dwordx4 v[104:107], v[8:9], off offset:192
	global_load_dwordx4 v[44:47], v[26:27], off offset:256
	global_load_dwordx4 v[108:111], v[8:9], off offset:256
	global_load_dwordx4 v[48:51], v[26:27], off offset:320
	global_load_dwordx4 v[112:115], v[8:9], off offset:320
	global_load_dwordx4 v[52:55], v[26:27], off offset:384
	global_load_dwordx4 v[116:119], v[8:9], off offset:384
	global_load_dwordx4 v[56:59], v[26:27], off offset:448
	global_load_dwordx4 v[120:123], v[8:9], off offset:448
	global_load_dwordx4 v[60:63], v[26:27], off offset:512
	global_load_dwordx4 v[124:127], v[8:9], off offset:512
	global_load_dwordx4 v[64:67], v[26:27], off offset:576
	global_load_dwordx4 v[128:131], v[8:9], off offset:576
	global_load_dwordx4 v[68:71], v[26:27], off offset:640
	global_load_dwordx4 v[132:135], v[8:9], off offset:640
	global_load_dwordx4 v[72:75], v[26:27], off offset:704
	global_load_dwordx4 v[136:139], v[8:9], off offset:704
	global_load_dwordx4 v[76:79], v[26:27], off offset:768
	global_load_dwordx4 v[140:143], v[8:9], off offset:768
	global_load_dwordx4 v[80:83], v[26:27], off offset:832
	global_load_dwordx4 v[144:147], v[8:9], off offset:832
	global_load_dwordx4 v[84:87], v[26:27], off offset:896
	global_load_dwordx4 v[180:183], v[8:9], off offset:896
	global_load_dwordx4 v[88:91], v[26:27], off offset:960
	global_load_dwordx4 v[184:187], v[8:9], off offset:960
	s_waitcnt vmcnt(30)
	v_mfma_f32_16x16x32_bf16 v[2:5], v[28:31], v[92:95], 0
	s_waitcnt vmcnt(28)
	v_mfma_f32_16x16x32_bf16 v[2:5], v[32:35], v[96:99], v[2:5]
	s_waitcnt vmcnt(26)
	v_mfma_f32_16x16x32_bf16 v[2:5], v[36:39], v[100:103], v[2:5]
	s_waitcnt vmcnt(24)
	v_mfma_f32_16x16x32_bf16 v[2:5], v[40:43], v[104:107], v[2:5]
	s_waitcnt vmcnt(22)
	v_mfma_f32_16x16x32_bf16 v[2:5], v[44:47], v[108:111], v[2:5]
	s_waitcnt vmcnt(20)
	v_mfma_f32_16x16x32_bf16 v[2:5], v[48:51], v[112:115], v[2:5]
	s_waitcnt vmcnt(18)
	v_mfma_f32_16x16x32_bf16 v[2:5], v[52:55], v[116:119], v[2:5]
	s_waitcnt vmcnt(16)
	v_mfma_f32_16x16x32_bf16 v[2:5], v[56:59], v[120:123], v[2:5]
	s_waitcnt vmcnt(14)
	v_mfma_f32_16x16x32_bf16 v[2:5], v[60:63], v[124:127], v[2:5]
	s_waitcnt vmcnt(12)
	v_mfma_f32_16x16x32_bf16 v[2:5], v[64:67], v[128:131], v[2:5]
	s_waitcnt vmcnt(10)
	v_mfma_f32_16x16x32_bf16 v[2:5], v[68:71], v[132:135], v[2:5]
	s_waitcnt vmcnt(8)
	v_mfma_f32_16x16x32_bf16 v[2:5], v[72:75], v[136:139], v[2:5]
	s_waitcnt vmcnt(6)
	v_mfma_f32_16x16x32_bf16 v[2:5], v[76:79], v[140:143], v[2:5]
	s_waitcnt vmcnt(4)
	v_mfma_f32_16x16x32_bf16 v[2:5], v[80:83], v[144:147], v[2:5]
	s_waitcnt vmcnt(2)
	v_mfma_f32_16x16x32_bf16 v[2:5], v[84:87], v[180:183], v[2:5]
	s_waitcnt vmcnt(0)
	v_mfma_f32_16x16x32_bf16 v[2:5], v[88:91], v[184:187], v[2:5]

; DI size_t zrowU(int row0, int NT) { return ((size_t)((row0 >> 8) * NT) << 16) + (size_t)((((row0 >> 7) & 1) << 15) | (((row0 >> 5) & 1) << 14) | (((row0 >> 6) & 1) << 11)); }
; DI unsigned zlaneRC(int r5, int col) { return (unsigned)(((col >> 8) << 16) | ((r5 >> 4) << 13) | (((col >> 7) & 1) << 12) | (((col >> 5) & 3) << 9) | (((col >> 3) & 3) << 7) | ((r5 & 15) << 3) | (col & 7)); }
; template <bool TILED_IN>
; DI void meta_gemm(const bf16_t* am, int lda, const bf16_t* Wt, int N, bf16_t* zo, int ldzo, int nt, LAS unsigned char* lds, int bid, int G, int wave, int lane) {
;     ...
;     for (int t0 = 2 * (G - 1 - bid); t0 < ntasks; t0 += 2 * G) {
;         const int task = t0 + (wave >> 2), n0 = task * 16;
;         const bf16_t* ap = Wt + (size_t)(n0 + r) * D + 8 * q + 512 * kq;
;         const bf16_t* bp = TILED_IN ? am + zrowU(SEQ, nt) + zlaneRC(r, 512 * kq + 8 * q) : am + (size_t)r * lda + 8 * q + 512 * kq;
;         f32x4 acc = {0.f, 0.f, 0.f, 0.f};
;         if (task < ntasks) {
; #pragma unroll
;             for (int k = 0; k < 16; ++k) { const bf16x8 a = *(const bf16x8*)(ap + 32 * k);
;                 const bf16x8 b = *(const bf16x8*)(bp + (TILED_IN ? (((k >> 3) << 16) | (((k >> 2) & 1) << 12) | ((k & 3) << 9)) : 32 * k));
;                 acc = __builtin_amdgcn_mfma_f32_16x16x32_bf16(a, b, acc, 0, 0, 0); }
;         }
.LBB0_296:
	s_add_i32 s6, s8, s23
	s_cmpk_gt_i32 s6, 0x7f
	s_cselect_b64 s[6:7], -1, 0
	v_mov_b32_e32 v2, 0
	s_and_b64 vcc, exec, s[6:7]
	v_mov_b32_e32 v3, 0
	v_mov_b32_e32 v4, 0
	v_mov_b32_e32 v5, 0
	s_cbranch_vccnz .LBB0_298
	v_add_u32_e32 v2, s10, v0
	v_ashrrev_i32_e32 v3, 31, v2
	v_lshlrev_b64 v[2:3], 12, v[2:3]
	v_lshl_add_u64 v[46:47], v[6:7], 0, v[2:3]
	global_load_dwordx4 v[48:51], v[46:47], off
	global_load_dwordx4 v[112:115], v[8:9], off
	global_load_dwordx4 v[52:55], v[46:47], off offset:64
	global_load_dwordx4 v[116:119], v[8:9], off offset:1024
	global_load_dwordx4 v[56:59], v[46:47], off offset:128
	global_load_dwordx4 v[120:123], v[8:9], off offset:2048
	global_load_dwordx4 v[60:63], v[46:47], off offset:192
	global_load_dwordx4 v[124:127], v[8:9], off offset:3072
	global_load_dwordx4 v[64:67], v[46:47], off offset:256
	global_load_dwordx4 v[128:131], v[12:13], off
	global_load_dwordx4 v[68:71], v[46:47], off offset:320
	global_load_dwordx4 v[132:135], v[14:15], off
	global_load_dwordx4 v[72:75], v[46:47], off offset:384
	global_load_dwordx4 v[136:139], v[16:17], off
	global_load_dwordx4 v[76:79], v[46:47], off offset:448
	global_load_dwordx4 v[140:143], v[18:19], off
	global_load_dwordx4 v[80:83], v[46:47], off offset:512
	global_load_dwordx4 v[144:147], v[20:21], off
	global_load_dwordx4 v[84:87], v[46:47], off offset:576
	global_load_dwordx4 v[178:181], v[22:23], off
	global_load_dwordx4 v[88:91], v[46:47], off offset:640
	global_load_dwordx4 v[182:185], v[24:25], off
	global_load_dwordx4 v[92:95], v[46:47], off offset:704
	global_load_dwordx4 v[186:189], v[26:27], off
	global_load_dwordx4 v[96:99], v[46:47], off offset:768
	global_load_dwordx4 v[190:193], v[28:29], off
	global_load_dwordx4 v[100:103], v[46:47], off offset:832
	global_load_dwordx4 v[194:197], v[30:31], off
	global_load_dwordx4 v[104:107], v[46:47], off offset:896
	global_load_dwordx4 v[198:201], v[32:33], off
	global_load_dwordx4 v[108:111], v[46:47], off offset:960
	global_load_dwordx4 v[202:205], v[34:35], off
	s_waitcnt vmcnt(30)
	v_mfma_f32_16x16x32_bf16 v[2:5], v[48:51], v[112:115], 0
	s_waitcnt vmcnt(28)
	v_mfma_f32_16x16x32_bf16 v[2:5], v[52:55], v[116:119], v[2:5]
	s_waitcnt vmcnt(26)
	v_mfma_f32_16x16x32_bf16 v[2:5], v[56:59], v[120:123], v[2:5]
	s_waitcnt vmcnt(24)
	v_mfma_f32_16x16x32_bf16 v[2:5], v[60:63], v[124:127], v[2:5]
	s_waitcnt vmcnt(22)
	v_mfma_f32_16x16x32_bf16 v[2:5], v[64:67], v[128:131], v[2:5]
	s_waitcnt vmcnt(20)
	v_mfma_f32_16x16x32_bf16 v[2:5], v[68:71], v[132:135], v[2:5]
	s_waitcnt vmcnt(18)
	v_mfma_f32_16x16x32_bf16 v[2:5], v[72:75], v[136:139], v[2:5]
	s_waitcnt vmcnt(16)
	v_mfma_f32_16x16x32_bf16 v[2:5], v[76:79], v[140:143], v[2:5]
	s_waitcnt vmcnt(14)
	v_mfma_f32_16x16x32_bf16 v[2:5], v[80:83], v[144:147], v[2:5]
	s_waitcnt vmcnt(12)
	v_mfma_f32_16x16x32_bf16 v[2:5], v[84:87], v[178:181], v[2:5]
	s_waitcnt vmcnt(10)
	v_mfma_f32_16x16x32_bf16 v[2:5], v[88:91], v[182:185], v[2:5]
	s_waitcnt vmcnt(8)
	v_mfma_f32_16x16x32_bf16 v[2:5], v[92:95], v[186:189], v[2:5]
	s_waitcnt vmcnt(6)
	v_mfma_f32_16x16x32_bf16 v[2:5], v[96:99], v[190:193], v[2:5]
	s_waitcnt vmcnt(4)
	v_mfma_f32_16x16x32_bf16 v[2:5], v[100:103], v[194:197], v[2:5]
	s_waitcnt vmcnt(2)
	v_mfma_f32_16x16x32_bf16 v[2:5], v[104:107], v[198:201], v[2:5]
	s_waitcnt vmcnt(0)
	v_mfma_f32_16x16x32_bf16 v[2:5], v[108:111], v[202:205], v[2:5]
